# code placement: two 4-byte pads in cold phase-entry code restore the baseline byte phase (mod 8) of the ph6a/ph7/ph8 GEMM mainloop heads (ph12a/ph13 kept)
# speedup vs baseline: 1.0043x; 1.0043x over previous
.LBB0_719:
	s_nop 0
	s_cmp_lt_i32 s74, 6
	s_cselect_b64 s[4:5], -1, 0
	s_and_b64 s[0:1], s[4:5], s[0:1]
	s_andn2_b64 vcc, exec, s[0:1]
	s_cbranch_vccnz .LBB0_727
	v_readlane_b32 s0, v254, 29
	s_cmpk_gt_i32 s0, 0x7fff
	s_movk_i32 s11, 0x7fff
	v_readlane_b32 s1, v254, 30
	s_cbranch_scc1 .LBB0_727
	v_lshlrev_b32_e32 v24, 5, v181
	v_mov_b32_e32 v25, 0
	s_waitcnt vmcnt(0)
	v_lshl_add_u64 v[20:21], s[44:45], 0, v[24:25]
	v_readlane_b32 s48, v254, 12
	v_add_co_u32_e32 v16, vcc, 0x1000, v20
	s_mov_b64 s[0:1], 0x1000
	v_readlane_b32 s58, v254, 22
	v_readlane_b32 s59, v254, 23
	v_readlane_b32 s60, v254, 24
	v_readlane_b32 s61, v254, 25
	v_addc_co_u32_e32 v17, vcc, 0, v21, vcc
	v_lshl_add_u64 v[20:21], v[20:21], 0, s[0:1]
	s_nop 0
	global_load_dwordx4 v[0:3], v24, s[58:59]
	s_nop 0
	global_load_dwordx4 v[4:7], v24, s[60:61]
	global_load_dwordx4 v[8:11], v24, s[60:61] offset:16
	global_load_dwordx4 v[12:15], v24, s[58:59] offset:16
	v_readlane_b32 s62, v254, 26
	global_load_dwordx4 v[16:19], v[16:17], off
	v_readlane_b32 s63, v254, 27
	global_load_dwordx4 v[20:23], v[20:21], off offset:16
	v_readlane_b32 s62, v254, 29
	v_readlane_b32 s63, v254, 30
	v_readlane_b32 s50, v254, 14
	v_readlane_b32 s51, v254, 15
	s_ashr_i32 s63, s62, 31
	v_lshrrev_b32_e32 v26, 1, v181
	v_readlane_b32 s54, v254, 18
	v_readlane_b32 s55, v254, 19
	v_readlane_b32 s56, v254, 20
	v_readlane_b32 s57, v254, 21
	v_and_b32_e32 v26, 28, v26
	v_mov_b32_e32 v27, v25
	s_lshl_b64 s[50:51], s[62:63], 5
	v_readlane_b32 s52, v254, 16
	v_readlane_b32 s53, v254, 17
	v_mov_b32_e32 v28, 0x1200
	s_mov_b64 s[2:3], 0x2880000
	v_lshlrev_b32_e32 v24, 4, v181
	s_lshl_b64 s[54:55], s[62:63], 10
	s_lshl_b64 s[56:57], s[62:63], 9
	s_lshl_b64 s[58:59], s[62:63], 12
	v_lshl_add_u64 v[56:57], s[62:63], 4, v[26:27]
	v_or_b32_e32 v26, s50, v26
	v_mov_b32_e32 v27, s51
	v_readlane_b32 s49, v254, 13
	s_ashr_i32 s35, s34, 31
	s_mov_b64 s[44:45], 0x1ad00000
	s_mov_b64 s[46:47], 0x7d00800
	s_lshl_b64 s[52:53], s[62:63], 11
	v_lshl_add_u64 v[54:55], s[42:43], 0, v[24:25]
	v_mad_i64_i32 v[58:59], s[60:61], s62, v28, v[24:25]
	v_or_b32_e32 v62, s54, v24
	v_lshl_add_u64 v[28:29], s[56:57], 0, v[24:25]
	v_or_b32_e32 v24, s58, v24
	v_mov_b32_e32 v25, s59
	v_lshl_add_u64 v[64:65], v[26:27], 0, s[2:3]
	s_mov_b32 s2, s62
	v_cmp_gt_u32_e64 s[0:1], 32, v181
	s_mul_hi_i32 s9, s34, 0x1200
	s_mul_i32 s8, s34, 0x1200
	s_mov_b64 s[16:17], 0x3d00000
	s_mov_b32 s14, 0x3d00000
	s_mov_b32 s15, 0xffff0000
	v_mov_b32_e32 v75, 0x3a27c5ac
	s_mov_b32 s48, 0x800000
	s_mov_b32 s49, 0xc2fc0000
	s_lshl_b64 s[18:19], s[34:35], 4
	s_lshl_b64 s[20:21], s[34:35], 5
	s_lshl_b64 s[22:23], s[34:35], 11
	s_lshl_b64 s[28:29], s[34:35], 10
	s_lshl_b64 s[30:31], s[34:35], 9
	s_lshl_b64 s[38:39], s[34:35], 12
	v_lshl_or_b32 v60, v181, 5, s52
	v_mov_b32_e32 v61, s53
	v_mov_b32_e32 v63, s55
	v_lshl_add_u64 v[66:67], v[28:29], 0, s[44:45]
	v_lshl_add_u64 v[68:69], v[24:25], 0, s[46:47]
	v_mov_b32_e32 v76, 0x42800000
	v_not_b32_e32 v77, 63
	v_writelane_b32 v254, s2, 29
	s_mov_b64 s[44:45], s[62:63]
	s_waitcnt vmcnt(5)
	v_mov_b32_e32 v70, v1
	v_mov_b32_e32 v71, v3
	s_waitcnt vmcnt(4)
	v_mov_b32_e32 v72, v5
	v_mov_b32_e32 v73, v7
	v_mov_b32_e32 v1, v2
	v_mov_b32_e32 v5, v6
	s_waitcnt vmcnt(2)
	v_mov_b32_e32 v2, v13
	v_mov_b32_e32 v3, v15
	v_mov_b32_e32 v6, v9
	v_mov_b32_e32 v7, v11
	v_mov_b32_e32 v13, v14
	v_mov_b32_e32 v9, v10
	s_waitcnt vmcnt(1)
	v_mov_b32_e32 v10, v17
	v_mov_b32_e32 v11, v19
	v_mov_b32_e32 v17, v18
	s_waitcnt vmcnt(0)
	v_mov_b32_e32 v14, v21
	v_mov_b32_e32 v15, v23
	v_mov_b32_e32 v21, v22
	v_writelane_b32 v254, s3, 30
	v_mov_b64_e32 v[100:101], v[60:61]
	v_mov_b64_e32 v[102:103], v[68:69]
	v_mov_b64_e32 v[104:105], v[62:63]
	v_mov_b64_e32 v[106:107], v[64:65]
	v_mov_b64_e32 v[108:109], v[58:59]
	v_mov_b64_e32 v[110:111], v[56:57]
	s_mov_b32 s98, s44
	s_mov_b32 s99, s45
	s_and_b32 s100, s98, 0xfff
	s_cmp_lg_u32 s100, 0
	s_cselect_b64 s[100:101], -1, 0
	v_cndmask_b32_e64 v118, 0, 1, s[100:101]
	v_mov_b32_e32 v119, s99
	v_sub_co_u32_e32 v118, vcc, s98, v118
	v_lshl_add_u64 v[122:123], s[72:73], 0, v[100:101]
	s_nop 0
	v_subbrev_co_u32_e32 v119, vcc, 0, v119, vcc
	v_lshl_add_u64 v[124:125], v[122:123], 0, s[16:17]
	v_add_co_u32_e32 v122, vcc, s14, v122
	v_lshlrev_b64 v[118:119], 12, v[118:119]
	s_nop 0
	v_addc_co_u32_e32 v123, vcc, 0, v123, vcc
	global_load_dwordx4 v[146:149], v[122:123], off
	global_load_dwordx4 v[134:137], v[124:125], off offset:16
	v_lshl_add_u64 v[122:123], s[72:73], 0, v[102:103]
	v_lshl_add_u64 v[118:119], v[54:55], 0, v[118:119]
	global_load_dwordx4 v[138:141], v[122:123], off
	global_load_dwordx4 v[150:153], v[118:119], off offset:2048
	v_lshl_add_u64 v[118:119], s[72:73], 0, v[104:105]
	v_add_co_u32_e32 v122, vcc, 0x1cd00000, v118
	v_lshl_add_u64 v[124:125], s[72:73], 0, v[106:107]
	s_nop 0
	v_addc_co_u32_e32 v123, vcc, 0, v119, vcc
	global_load_dwordx4 v[142:145], v[122:123], off
	global_load_dword v174, v[124:125], off
	v_mov_b32_e32 v126, 0
	v_mov_b32_e32 v178, 0
	v_mov_b32_e32 v179, 0
	v_mov_b32_e32 v180, 0
	v_mov_b32_e32 v127, 0
	v_mov_b32_e32 v128, 0
	v_mov_b32_e32 v129, 0
	v_mov_b32_e32 v122, 0
	v_mov_b32_e32 v123, 0
	v_mov_b32_e32 v124, 0
	v_mov_b32_e32 v125, 0
	v_mov_b32_e32 v130, 0
	v_mov_b32_e32 v131, 0
	v_mov_b32_e32 v132, 0
	v_mov_b32_e32 v133, 0
	s_and_saveexec_b64 s[46:47], s[0:1]
	s_cbranch_execz .Lmy_p5_a
	v_lshl_add_u64 v[122:123], s[72:73], 0, v[108:109]
	v_add_co_u32_e32 v126, vcc, 0xfd00000, v122
	v_lshl_add_u64 v[128:129], s[72:73], 0, v[110:111]
	s_nop 0
	v_addc_co_u32_e32 v127, vcc, 0, v123, vcc
	v_add_co_u32_e32 v178, vcc, 0x2b80000, v128
	global_load_dwordx4 v[130:133], v[126:127], off
	global_load_dwordx4 v[122:125], v[126:127], off offset:512
	v_addc_co_u32_e32 v179, vcc, 0, v129, vcc
	v_add_co_u32_e32 v182, vcc, 0x2c00000, v128
	s_nop 1
	v_addc_co_u32_e32 v183, vcc, 0, v129, vcc
	v_add_co_u32_e32 v184, vcc, 0x2c80000, v128
	s_nop 1
	v_addc_co_u32_e32 v185, vcc, 0, v129, vcc
	global_load_dwordx4 v[126:129], v[126:127], off offset:1024
	s_nop 0
	global_load_dword v180, v[178:179], off
	s_nop 0
	global_load_dword v179, v[182:183], off
	global_load_dword v178, v[184:185], off

.LBB0_1057:
	s_nop 0
	s_cmp_lt_i32 s74, 10
	s_cselect_b64 s[4:5], -1, 0
	s_and_b64 s[0:1], s[4:5], s[0:1]
	s_andn2_b64 vcc, exec, s[0:1]
	s_cbranch_vccnz .LBB0_1062
	s_mov_b32 s11, 0xc000
	v_cmp_gt_i32_e32 vcc, s11, v162
	s_and_saveexec_b64 s[6:7], vcc
	s_cbranch_execz .LBB0_1061
	s_add_u32 s8, s72, 0xbd00000
	s_addc_u32 s9, s73, 0
	s_add_u32 s0, s72, 0xc400000
	s_addc_u32 s1, s73, 0
	s_add_u32 s22, s24, 0x6000
	s_addc_u32 s23, s25, 0
	s_add_u32 s28, s24, 0xc000
	s_waitcnt vmcnt(0)
	v_lshlrev_b32_e32 v0, 3, v210
	s_mov_b64 s[20:21], 0x6000
	s_addc_u32 s29, s25, 0
	v_lshl_add_u32 v6, s10, 12, v0
	s_lshl_b32 s14, s33, 12
	s_mov_b64 s[30:31], 0
	s_mov_b32 s15, 0x2aaaaaab
	s_waitcnt lgkmcnt(0)
	v_mov_b64_e32 v[0:1], s[0:1]
	s_movk_i32 s38, 0x6000
	s_mov_b64 s[34:35], 0x6200
	s_mov_b64 s[36:37], 0x3000
	s_movk_i32 s39, 0x3000
	v_mov_b32_e32 v7, 0xc0135761
	s_movk_i32 s44, 0x7fff
	s_mov_b32 s45, 0xffff0000
	s_mov_b32 s46, 0xbfff
